# MoBA: q row prefetched for gate scores, tile descriptors read between step barriers; K and V LDS fragment reads hoisted in all attention tiles
# speedup vs baseline: 1.0312x; 1.0062x over previous
.LBB0_344:
	s_or_b64 exec, exec, s[2:3]
	v_cmp_gt_i32_e32 vcc, 16, v3
	s_and_saveexec_b64 s[2:3], vcc
	v_lshlrev_b32_e32 v0, 2, v3
	ds_write_b32 v0, v2 offset:56832
	s_or_b64 exec, exec, s[2:3]
	v_and_b32_e32 v34, 1, v8
	v_readlane_b32 s2, v249, 36
	v_lshlrev_b32_e32 v19, 7, v34
	v_ashrrev_i32_e32 v20, 1, v3
	v_lshl_add_u32 v15, v7, 8, s2
	v_or_b32_e32 v128, v15, v19
	v_add_u32_e32 v4, v20, v128
	v_mov_b64_e32 v[0:1], s[4:5]
	v_and_b32_e32 v21, 1, v3
	v_mad_i64_i32 v[0:1], s[2:3], v4, s93, v[0:1]
	v_lshlrev_b32_e32 v4, 1, v32
	v_mov_b32_e32 v5, v2
	v_lshl_add_u64 v[0:1], v[0:1], 0, v[4:5]
	global_load_dwordx4 v[154:157], v[0:1], off
	global_load_dwordx4 v[158:161], v[0:1], off offset:16
	global_load_dwordx4 v[162:165], v[0:1], off offset:32
	global_load_dwordx4 v[166:169], v[0:1], off offset:48
	global_load_dwordx4 v[170:173], v[0:1], off offset:64
	global_load_dwordx4 v[174:177], v[0:1], off offset:80
	global_load_dwordx4 v[178:181], v[0:1], off offset:96
	global_load_dwordx4 v[182:185], v[0:1], off offset:112
	v_or_b32_e32 v4, 2, v21
	v_cmp_lt_u32_e64 s[40:41], v4, v7
	v_or_b32_e32 v4, 4, v21
	v_cmp_lt_u32_e64 s[42:43], v4, v7
	v_or_b32_e32 v4, 6, v21
	v_cmp_lt_u32_e64 s[44:45], v4, v7
	v_or_b32_e32 v4, 8, v21
	v_cmp_lt_u32_e64 s[46:47], v4, v7
	v_or_b32_e32 v4, 10, v21
	v_cmp_lt_u32_e64 s[48:49], v4, v7
	v_or_b32_e32 v4, 12, v21
	v_cmp_lt_u32_e64 s[50:51], v4, v7
	v_or_b32_e32 v4, 14, v21
	v_cmp_lt_u32_e64 s[38:39], v21, v7
	v_cmp_lt_u32_e64 s[52:53], v4, v7
	v_lshl_or_b32 v22, v21, 8, v210
	v_mov_b32_e32 v24, 0
	s_mov_b32 s8, 0
	v_mov_b32_e32 v25, 0
	v_mov_b32_e32 v26, 0
	v_mov_b32_e32 v27, 0
	v_mov_b32_e32 v28, 0
	v_mov_b32_e32 v29, 0
	v_mov_b32_e32 v30, 0
	v_mov_b32_e32 v23, 0
	s_waitcnt lgkmcnt(0)
	s_barrier
	s_branch .LBB0_348

.LBB0_348:
	v_add_u32_e32 v31, s8, v22
	s_cmp_eq_u32 s8, 0
	s_cbranch_scc1 .Lmq_0
	s_cmp_eq_u32 s8, 32
	s_cbranch_scc1 .Lmq_1
	s_cmp_eq_u32 s8, 64
	s_cbranch_scc1 .Lmq_2
	s_cmp_eq_u32 s8, 96
	s_cbranch_scc1 .Lmq_3
	s_cmp_eq_u32 s8, 128
	s_cbranch_scc1 .Lmq_4
	s_cmp_eq_u32 s8, 160
	s_cbranch_scc1 .Lmq_5
	s_cmp_eq_u32 s8, 192
	s_cbranch_scc1 .Lmq_6
	s_waitcnt vmcnt(0)
	v_mov_b64_e32 v[36:37], v[182:183]
	v_mov_b64_e32 v[38:39], v[184:185]
	s_branch .Lmq_done
.Lmq_0:
	s_waitcnt vmcnt(7)
	v_mov_b64_e32 v[36:37], v[154:155]
	v_mov_b64_e32 v[38:39], v[156:157]
	s_branch .Lmq_done
.Lmq_1:
	s_waitcnt vmcnt(6)
	v_mov_b64_e32 v[36:37], v[158:159]
	v_mov_b64_e32 v[38:39], v[160:161]
	s_branch .Lmq_done
.Lmq_2:
	s_waitcnt vmcnt(5)
	v_mov_b64_e32 v[36:37], v[162:163]
	v_mov_b64_e32 v[38:39], v[164:165]
	s_branch .Lmq_done
.Lmq_3:
	s_waitcnt vmcnt(4)
	v_mov_b64_e32 v[36:37], v[166:167]
	v_mov_b64_e32 v[38:39], v[168:169]
	s_branch .Lmq_done
.Lmq_4:
	s_waitcnt vmcnt(3)
	v_mov_b64_e32 v[36:37], v[170:171]
	v_mov_b64_e32 v[38:39], v[172:173]
	s_branch .Lmq_done
.Lmq_5:
	s_waitcnt vmcnt(2)
	v_mov_b64_e32 v[36:37], v[174:175]
	v_mov_b64_e32 v[38:39], v[176:177]
	s_branch .Lmq_done
.Lmq_6:
	s_waitcnt vmcnt(1)
	v_mov_b64_e32 v[36:37], v[178:179]
	v_mov_b64_e32 v[38:39], v[180:181]
.Lmq_done:
	v_lshlrev_b32_e32 v12, 16, v36
	v_and_b32_e32 v13, 0xffff0000, v36
	v_lshlrev_b32_e32 v16, 16, v37
	v_and_b32_e32 v17, 0xffff0000, v37
	v_lshlrev_b32_e32 v8, 16, v38
	v_and_b32_e32 v9, 0xffff0000, v38
	v_lshlrev_b32_e32 v4, 16, v39
	v_and_b32_e32 v5, 0xffff0000, v39
	s_and_saveexec_b64 s[2:3], s[38:39]
	s_cbranch_execnz .LBB0_356
	s_or_b64 exec, exec, s[2:3]
	s_and_saveexec_b64 s[2:3], s[40:41]
	s_cbranch_execnz .LBB0_357

.LBB0_404:
	s_andn2_saveexec_b64 s[2:3], s[2:3]
	s_or_b64 exec, exec, s[2:3]
	v_max3_f32 v126, v133, v139, v140
	v_sub_f32_e32 v127, v133, v126
	v_mul_f32_e32 v133, 0x3e38aa3b, v126
	v_cmp_ngt_f32_e32 vcc, s36, v126
	v_mul_f32_e32 v127, 0x3e38aa3b, v127
	s_nop 0
	v_cndmask_b32_e32 v133, 0, v133, vcc
	v_fma_f32 v120, v120, s29, -v133
	v_exp_f32_e32 v137, v120
	v_fma_f32 v121, v121, s29, -v133
	v_exp_f32_e32 v138, v121
	v_fma_f32 v121, v122, s29, -v133
	v_exp_f32_e32 v139, v121
	v_fma_f32 v121, v123, s29, -v133
	v_exp_f32_e32 v140, v121
	v_fma_f32 v116, v116, s29, -v133
	v_add_f32_e32 v120, 0, v137
	v_exp_f32_e32 v141, v116
	v_add_f32_e32 v120, v138, v120
	v_add_f32_e32 v120, v139, v120
	v_fma_f32 v117, v117, s29, -v133
	v_add_f32_e32 v120, v140, v120
	v_exp_f32_e32 v142, v117
	v_fma_f32 v117, v118, s29, -v133
	v_fma_f32 v108, v108, s29, -v133
	v_fma_f32 v109, v109, s29, -v133
	v_add_f32_e32 v116, v141, v120
	v_exp_f32_e32 v143, v117
	v_fma_f32 v117, v119, s29, -v133
	v_exp_f32_e32 v119, v108
	v_exp_f32_e32 v120, v109
	v_fma_f32 v109, v110, s29, -v133
	v_exp_f32_e32 v118, v127
	v_exp_f32_e32 v121, v109
	v_fma_f32 v109, v111, s29, -v133
	v_exp_f32_e32 v122, v109
	v_fma_f32 v109, v112, s29, -v133
	v_exp_f32_e32 v123, v109
	v_fma_f32 v109, v113, s29, -v133
	v_exp_f32_e32 v145, v109
	v_fma_f32 v109, v114, s29, -v133
	v_pk_mul_f32 v[112:113], v[80:81], v[118:119] op_sel_hi:[1,0]
	v_pk_mul_f32 v[80:81], v[84:85], v[118:119] op_sel_hi:[1,0]
	v_max_f32_e32 v84, v103, v103
	v_max_f32_e32 v85, v102, v102
	v_exp_f32_e32 v146, v109
	v_fma_f32 v109, v115, s29, -v133
	v_pk_mul_f32 v[114:115], v[82:83], v[118:119] op_sel_hi:[1,0]
	v_pk_mul_f32 v[82:83], v[86:87], v[118:119] op_sel_hi:[1,0]
	v_max_f32_e32 v84, v85, v84
	v_max_f32_e32 v85, v99, v99
	v_max_f32_e32 v86, v98, v98
	v_exp_f32_e32 v144, v117
	v_max_f32_e32 v85, v86, v85
	v_max3_f32 v84, v100, v101, v84
	v_max3_f32 v85, v96, v97, v85
	v_add_f32_e32 v116, v142, v116
	v_max3_f32 v84, v84, s28, v85
	v_max_f32_e32 v85, v95, v95
	v_max_f32_e32 v86, v94, v94
	v_add_f32_e32 v116, v143, v116
	v_max_f32_e32 v85, v86, v85
	v_max_f32_e32 v86, v107, v107
	v_max_f32_e32 v87, v106, v106
	v_add_f32_e32 v116, v144, v116
	v_max_f32_e32 v86, v87, v86
	v_add_f32_e32 v108, v119, v116
	v_max3_f32 v85, v92, v93, v85
	v_max3_f32 v86, v104, v105, v86
	v_add_f32_e32 v108, v120, v108
	v_max3_f32 v84, v84, v85, v86
	v_add_f32_e32 v108, v121, v108
	v_mov_b32_e32 v85, v84
	v_add_f32_e32 v108, v122, v108
	v_exp_f32_e32 v133, v109
	v_permlane16_swap_b32_e32 v84, v85
	v_add_f32_e32 v108, v123, v108
	v_max_f32_e32 v85, v85, v85
	v_max_f32_e32 v84, v84, v84
	v_add_f32_e32 v108, v145, v108
	v_max_f32_e32 v84, v84, v85
	v_add_f32_e32 v108, v146, v108
	v_mov_b32_e32 v85, v84
	v_add_f32_e32 v116, v133, v108
	s_nop 0
	v_permlane32_swap_b32_e32 v84, v85
	v_fmac_f32_e32 v116, v124, v118
	v_pk_mul_f32 v[110:111], v[78:79], v[118:119] op_sel_hi:[1,0]
	v_pk_mul_f32 v[108:109], v[76:77], v[118:119] op_sel_hi:[1,0]
	v_pk_mul_f32 v[78:79], v[90:91], v[118:119] op_sel_hi:[1,0]
	v_pk_mul_f32 v[76:77], v[88:89], v[118:119] op_sel_hi:[1,0]
	v_max3_f32 v118, v1, v84, v85
	v_mul_f32_e32 v84, 0x3e38aa3b, v118
	v_cmp_ngt_f32_e32 vcc, s36, v118
	v_sub_f32_e32 v1, v1, v118
	v_mul_f32_e32 v1, 0x3e38aa3b, v1
	v_cndmask_b32_e32 v84, 0, v84, vcc
	v_fma_f32 v85, v100, s29, -v84
	v_exp_f32_e32 v88, v85
	v_fma_f32 v86, v101, s29, -v84
	v_exp_f32_e32 v89, v86
	v_fma_f32 v86, v102, s29, -v84
	v_exp_f32_e32 v90, v86
	v_fma_f32 v86, v103, s29, -v84
	v_exp_f32_e32 v91, v86
	v_fma_f32 v86, v96, s29, -v84
	v_add_f32_e32 v85, 0, v88
	v_exp_f32_e32 v96, v86
	v_fma_f32 v86, v97, s29, -v84
	v_add_f32_e32 v85, v89, v85
	v_exp_f32_e32 v97, v86
	v_fma_f32 v86, v98, s29, -v84
	v_add_f32_e32 v85, v90, v85
	v_exp_f32_e32 v98, v86
	v_fma_f32 v86, v99, s29, -v84
	v_add_f32_e32 v85, v91, v85
	v_exp_f32_e32 v99, v86
	v_fma_f32 v86, v92, s29, -v84
	v_add_f32_e32 v85, v96, v85
	v_exp_f32_e32 v124, v86
	v_fma_f32 v86, v93, s29, -v84
	v_add_f32_e32 v85, v97, v85
	v_exp_f32_e32 v127, v86
	v_fma_f32 v86, v94, s29, -v84
	v_add_f32_e32 v85, v98, v85
	v_exp_f32_e32 v147, v86
	v_fma_f32 v86, v95, s29, -v84
	v_add_f32_e32 v85, v99, v85
	v_exp_f32_e32 v148, v86
	v_fma_f32 v86, v104, s29, -v84
	v_add_f32_e32 v85, v124, v85
	v_exp_f32_e32 v149, v86
	v_fma_f32 v86, v105, s29, -v84
	v_add_f32_e32 v85, v127, v85
	v_exp_f32_e32 v150, v86
	v_fma_f32 v86, v106, s29, -v84
	v_add_f32_e32 v85, v147, v85
	v_exp_f32_e32 v151, v86
	v_fma_f32 v84, v107, s29, -v84
	v_add_f32_e32 v85, v148, v85
	v_exp_f32_e32 v152, v84
	v_add_f32_e32 v85, v149, v85
	v_exp_f32_e32 v84, v1
	v_add_f32_e32 v85, v150, v85
	v_add_f32_e32 v85, v151, v85
	v_add_f32_e32 v117, v152, v85
	v_fmac_f32_e32 v117, v125, v84
	v_pk_mul_f32 v[62:63], v[62:63], v[84:85] op_sel_hi:[1,0]
	v_pk_mul_f32 v[60:61], v[60:61], v[84:85] op_sel_hi:[1,0]
	v_pk_mul_f32 v[66:67], v[66:67], v[84:85] op_sel_hi:[1,0]
	v_pk_mul_f32 v[64:65], v[64:65], v[84:85] op_sel_hi:[1,0]
	v_pk_mul_f32 v[70:71], v[70:71], v[84:85] op_sel_hi:[1,0]
	v_pk_mul_f32 v[68:69], v[68:69], v[84:85] op_sel_hi:[1,0]
	v_pk_mul_f32 v[74:75], v[74:75], v[84:85] op_sel_hi:[1,0]
	v_pk_mul_f32 v[72:73], v[72:73], v[84:85] op_sel_hi:[1,0]
	v_lshrrev_b32_e32 v1, 2, v135
	v_lshlrev_b32_e32 v84, 3, v134
	v_or_b32_e32 v1, v136, v1
	v_and_b32_e32 v92, 24, v84
	v_mad_i32_i24 v1, v1, s0, v92
	v_cvt_pk_bf16_f32 v88, v88, v89
	v_cvt_pk_bf16_f32 v89, v90, v91
	v_cvt_pk_bf16_f32 v90, v96, v97
	v_cvt_pk_bf16_f32 v91, v98, v99
	ds_read_b64_tr_b16 v[162:163], v1 offset:11520
	ds_read_b64_tr_b16 v[160:161], v1 offset:9216
	ds_read_b64_tr_b16 v[164:165], v1 offset:9248
	ds_read_b64_tr_b16 v[166:167], v1 offset:11552
	ds_read_b64_tr_b16 v[168:169], v1 offset:9280
	ds_read_b64_tr_b16 v[170:171], v1 offset:11584
	ds_read_b64_tr_b16 v[172:173], v1 offset:9312
	ds_read_b64_tr_b16 v[174:175], v1 offset:11616
	ds_read_b64_tr_b16 v[176:177], v1 offset:13824
	ds_read_b64_tr_b16 v[178:179], v1 offset:16128
	ds_read_b64_tr_b16 v[180:181], v1 offset:13856
	ds_read_b64_tr_b16 v[182:183], v1 offset:16160
	ds_read_b64_tr_b16 v[184:185], v1 offset:13888
	ds_read_b64_tr_b16 v[186:187], v1 offset:16192
	ds_read_b64_tr_b16 v[188:189], v1 offset:13920
	ds_read_b64_tr_b16 v[190:191], v1 offset:16224
	v_cvt_pk_bf16_f32 v84, v137, v138
	v_cvt_pk_bf16_f32 v85, v139, v140
	v_cvt_pk_bf16_f32 v86, v141, v142
	v_cvt_pk_bf16_f32 v87, v143, v144
	s_waitcnt lgkmcnt(14)
	v_mfma_f32_16x16x32_bf16 v[60:63], v[160:163], v[88:91], v[60:63]
	v_mov_b32_e32 v125, v117
	v_mfma_f32_16x16x32_bf16 v[100:103], v[160:163], v[84:87], v[108:111]
	s_waitcnt lgkmcnt(12)
	v_mfma_f32_16x16x32_bf16 v[92:95], v[164:167], v[84:87], v[112:115]
	s_nop 0
	v_cvt_pk_bf16_f32 v108, v124, v127
	v_cvt_pk_bf16_f32 v109, v147, v148
	v_cvt_pk_bf16_f32 v110, v149, v150
	v_mfma_f32_16x16x32_bf16 v[64:67], v[164:167], v[88:91], v[64:67]
	v_cvt_pk_bf16_f32 v111, v151, v152
	v_mov_b32_e32 v124, v116
	s_waitcnt lgkmcnt(10)
	v_mfma_f32_16x16x32_bf16 v[104:107], v[168:171], v[84:87], v[80:83]
	s_nop 2
	v_mfma_f32_16x16x32_bf16 v[68:71], v[168:171], v[88:91], v[68:71]
	s_waitcnt lgkmcnt(8)
	v_mfma_f32_16x16x32_bf16 v[96:99], v[172:175], v[84:87], v[76:79]
	v_mfma_f32_16x16x32_bf16 v[72:75], v[172:175], v[88:91], v[72:75]
	v_cvt_pk_bf16_f32 v88, v119, v120
	v_cvt_pk_bf16_f32 v89, v121, v122
	v_cvt_pk_bf16_f32 v90, v123, v145
	v_cvt_pk_bf16_f32 v91, v146, v133
	s_waitcnt lgkmcnt(6)
	v_mfma_f32_16x16x32_bf16 v[60:63], v[176:179], v[108:111], v[60:63]
	v_mov_b32_e32 v133, v126
	v_mfma_f32_16x16x32_bf16 v[76:79], v[176:179], v[88:91], v[100:103]
	s_waitcnt lgkmcnt(4)
	v_mfma_f32_16x16x32_bf16 v[80:83], v[180:183], v[88:91], v[92:95]
	s_nop 2
	v_mfma_f32_16x16x32_bf16 v[64:67], v[180:183], v[108:111], v[64:67]
	s_waitcnt lgkmcnt(2)
	v_mfma_f32_16x16x32_bf16 v[84:87], v[184:187], v[88:91], v[104:107]
	v_mfma_f32_16x16x32_bf16 v[68:71], v[184:187], v[108:111], v[68:71]
	v_mov_b32_e32 v1, v118
	s_waitcnt lgkmcnt(0)
	v_mfma_f32_16x16x32_bf16 v[88:91], v[188:191], v[88:91], v[96:99]
	v_mfma_f32_16x16x32_bf16 v[72:75], v[188:191], v[108:111], v[72:75]

.LBB0_408:
	v_mov_b32_e32 v92, s15
	ds_read2_b32 v[126:127], v92 offset1:1
	v_mov_b64_e32 v[116:117], v[124:125]
	s_waitcnt lgkmcnt(0)
	v_cmp_ge_i32_e32 vcc, v131, v126
	v_cmp_le_i32_e64 s[38:39], v132, v127
	s_and_b64 s[2:3], vcc, s[38:39]
	s_and_saveexec_b64 s[50:51], s[2:3]
	s_cbranch_execz .LBB0_405
	v_mov_b32_e32 v134, v197
	v_cmp_lt_i32_e32 vcc, v132, v126
	v_and_b32_e32 v135, 15, v134
	v_mul_u32_u24_e32 v92, 0x48, v135
	v_bfe_u32 v137, v134, 4, 2
	v_lshlrev_b32_e32 v92, 1, v92
	v_lshl_add_u32 v136, v137, 4, v92
	ds_read_b128 v[160:163], v136 offset:2304
	ds_read_b128 v[164:167], v136 offset:0
	ds_read_b128 v[168:171], v136 offset:4608
	ds_read_b128 v[172:175], v136 offset:6912
	ds_read_b128 v[176:179], v136 offset:64
	ds_read_b128 v[180:183], v136 offset:2368
	ds_read_b128 v[184:187], v136 offset:6976
	ds_read_b128 v[188:191], v136 offset:4672
	v_cmp_gt_i32_e64 s[38:39], v131, v127
	s_or_b64 s[2:3], vcc, s[38:39]
	s_waitcnt vmcnt(3)
	s_waitcnt lgkmcnt(7)
	v_mfma_f32_16x16x32_bf16 v[104:107], v[160:163], v[44:47], 0
	s_waitcnt vmcnt(1)
	v_mfma_f32_16x16x32_bf16 v[108:111], v[160:163], v[52:55], 0
	s_waitcnt lgkmcnt(5)
	v_mfma_f32_16x16x32_bf16 v[112:115], v[168:171], v[44:47], 0
	v_mfma_f32_16x16x32_bf16 v[138:141], v[168:171], v[52:55], 0
	s_waitcnt lgkmcnt(4)
	v_mfma_f32_16x16x32_bf16 v[142:145], v[172:175], v[44:47], 0
	v_mfma_f32_16x16x32_bf16 v[146:149], v[172:175], v[52:55], 0
	v_mfma_f32_16x16x32_bf16 v[96:99], v[164:167], v[44:47], 0
	v_mfma_f32_16x16x32_bf16 v[92:95], v[164:167], v[52:55], 0
	s_waitcnt lgkmcnt(3)
	v_mfma_f32_16x16x32_bf16 v[120:123], v[176:179], v[48:51], v[96:99]
	s_waitcnt vmcnt(0)
	v_mfma_f32_16x16x32_bf16 v[100:103], v[176:179], v[56:59], v[92:95]
	s_nop 3
	s_waitcnt lgkmcnt(2)
	v_mfma_f32_16x16x32_bf16 v[116:119], v[180:183], v[48:51], v[104:107]
	s_nop 2
	v_mfma_f32_16x16x32_bf16 v[96:99], v[180:183], v[56:59], v[108:111]
	v_lshlrev_b32_e32 v136, 2, v137
	s_waitcnt lgkmcnt(0)
	v_mfma_f32_16x16x32_bf16 v[108:111], v[188:191], v[48:51], v[112:115]
	v_mfma_f32_16x16x32_bf16 v[92:95], v[188:191], v[56:59], v[138:141]
	v_mfma_f32_16x16x32_bf16 v[112:115], v[184:187], v[48:51], v[142:145]
	s_nop 1
	v_or_b32_e32 v138, v135, v130
	v_mfma_f32_16x16x32_bf16 v[104:107], v[184:187], v[56:59], v[146:149]
	s_and_saveexec_b64 s[8:9], s[2:3]
	s_cbranch_execz .LBB0_411
	v_lshlrev_b32_e32 v139, 2, v137
	v_sub_u32_e32 v140, v138, v139
	v_cmp_ge_i32_e32 vcc, v140, v126
	v_cmp_le_i32_e64 s[38:39], v140, v127
	s_and_b64 vcc, vcc, s[38:39]
	v_xad_u32 v140, v139, -1, v138
	v_cndmask_b32_e32 v120, v212, v120, vcc
	v_cmp_ge_i32_e32 vcc, v140, v126
	v_cmp_le_i32_e64 s[38:39], v140, v127
	v_or_b32_e32 v140, 2, v139
	s_and_b64 vcc, vcc, s[38:39]
	v_sub_u32_e32 v140, v138, v140
	v_cndmask_b32_e32 v121, v212, v121, vcc
	v_cmp_ge_i32_e32 vcc, v140, v126
	v_cmp_le_i32_e64 s[38:39], v140, v127
	v_or_b32_e32 v140, 3, v139
	s_and_b64 vcc, vcc, s[38:39]
	v_sub_u32_e32 v140, v138, v140
	v_cndmask_b32_e32 v122, v212, v122, vcc
	v_cmp_ge_i32_e32 vcc, v140, v126
	v_cmp_le_i32_e64 s[38:39], v140, v127
	v_or_b32_e32 v140, 16, v139
	s_and_b64 vcc, vcc, s[38:39]
	v_sub_u32_e32 v140, v138, v140
	v_cndmask_b32_e32 v123, v212, v123, vcc
	v_cmp_ge_i32_e32 vcc, v140, v126
	v_cmp_le_i32_e64 s[38:39], v140, v127
	v_or_b32_e32 v140, 17, v139
	s_and_b64 vcc, vcc, s[38:39]
	v_sub_u32_e32 v140, v138, v140
	v_cndmask_b32_e32 v116, v212, v116, vcc
	v_cmp_ge_i32_e32 vcc, v140, v126
	v_cmp_le_i32_e64 s[38:39], v140, v127
	v_or_b32_e32 v140, 18, v139
	s_and_b64 vcc, vcc, s[38:39]
	v_sub_u32_e32 v140, v138, v140
	v_cndmask_b32_e32 v117, v212, v117, vcc
	v_cmp_ge_i32_e32 vcc, v140, v126
	v_cmp_le_i32_e64 s[38:39], v140, v127
	v_or_b32_e32 v140, 19, v139
	s_and_b64 vcc, vcc, s[38:39]
	v_sub_u32_e32 v140, v138, v140
	v_cndmask_b32_e32 v118, v212, v118, vcc
	v_cmp_ge_i32_e32 vcc, v140, v126
	v_cmp_le_i32_e64 s[38:39], v140, v127
	v_or_b32_e32 v140, 32, v139
	s_and_b64 vcc, vcc, s[38:39]
	v_sub_u32_e32 v140, v138, v140
	v_cndmask_b32_e32 v119, v212, v119, vcc
	v_cmp_ge_i32_e32 vcc, v140, v126
	v_cmp_le_i32_e64 s[38:39], v140, v127
	v_or_b32_e32 v140, 33, v139
	s_and_b64 vcc, vcc, s[38:39]
	v_sub_u32_e32 v140, v138, v140
	v_cndmask_b32_e32 v108, v212, v108, vcc
	v_cmp_ge_i32_e32 vcc, v140, v126
	v_cmp_le_i32_e64 s[38:39], v140, v127
	v_or_b32_e32 v140, 34, v139
	s_and_b64 vcc, vcc, s[38:39]
	v_sub_u32_e32 v140, v138, v140
	v_cndmask_b32_e32 v109, v212, v109, vcc
	v_cmp_ge_i32_e32 vcc, v140, v126
	v_cmp_le_i32_e64 s[38:39], v140, v127
	v_or_b32_e32 v140, 35, v139
	s_and_b64 vcc, vcc, s[38:39]
	v_sub_u32_e32 v140, v138, v140
	v_cndmask_b32_e32 v110, v212, v110, vcc
	v_cmp_ge_i32_e32 vcc, v140, v126
	v_cmp_le_i32_e64 s[38:39], v140, v127
	v_or_b32_e32 v140, 48, v139
	s_and_b64 vcc, vcc, s[38:39]
	v_sub_u32_e32 v140, v138, v140
	v_cndmask_b32_e32 v111, v212, v111, vcc
	v_cmp_ge_i32_e32 vcc, v140, v126
	v_cmp_le_i32_e64 s[38:39], v140, v127
	v_or_b32_e32 v140, 49, v139
	s_and_b64 vcc, vcc, s[38:39]
	v_sub_u32_e32 v140, v138, v140
	v_cndmask_b32_e32 v112, v212, v112, vcc
	v_cmp_ge_i32_e32 vcc, v140, v126
	v_cmp_le_i32_e64 s[38:39], v140, v127
	v_or_b32_e32 v140, 50, v139
	s_and_b64 vcc, vcc, s[38:39]
	v_sub_u32_e32 v140, v138, v140
	v_cndmask_b32_e32 v113, v212, v113, vcc
	v_cmp_ge_i32_e32 vcc, v140, v126
	v_cmp_le_i32_e64 s[38:39], v140, v127
	v_or_b32_e32 v139, 51, v139
	s_and_b64 vcc, vcc, s[38:39]
	v_sub_u32_e32 v139, v138, v139
	v_cndmask_b32_e32 v114, v212, v114, vcc
	v_cmp_ge_i32_e32 vcc, v139, v126
	v_cmp_le_i32_e64 s[38:39], v139, v127
	s_and_b64 vcc, vcc, s[38:39]
	v_cndmask_b32_e32 v115, v212, v115, vcc

.LBB0_423:
	s_add_i32 s16, s10, 1
	s_cmp_ge_i32 s16, s14
	s_cselect_b64 s[40:41], -1, 0
	s_and_b64 vcc, exec, s[40:41]
	s_waitcnt lgkmcnt(0)
	s_barrier
	v_mov_b32_e32 v52, s15
	ds_read_b32 v77, v52
	ds_read_b32 v153, v52 offset:8
	s_waitcnt vmcnt(2)
	ds_write_b128 v5, v[24:27]
	ds_write_b128 v5, v[20:23] offset:16
	s_waitcnt vmcnt(0)
	ds_write_b128 v5, v[32:35] offset:9216
	ds_write_b128 v5, v[28:31] offset:9232
	s_waitcnt lgkmcnt(0)
	s_barrier
	s_cbranch_vccnz .LBB0_425
	v_add_u32_e32 v20, v153, v7
	v_mad_i64_i32 v[32:33], s[2:3], v20, s93, v[12:13]
	global_load_dwordx4 v[20:23], v[32:33], off offset:528
	global_load_dwordx4 v[24:27], v[32:33], off offset:512
	global_load_dwordx4 v[28:31], v[32:33], off offset:1040
	s_nop 0
	global_load_dwordx4 v[32:35], v[32:33], off offset:1024
.LBB0_425:
	v_cmp_ne_u32_e32 vcc, 0, v77
	s_cbranch_vccz .LBB0_427
	v_mov_b64_e32 v[58:59], v[42:43]
	v_mov_b64_e32 v[54:55], v[38:39]
	v_mov_b64_e32 v[56:57], v[40:41]
	v_mov_b64_e32 v[52:53], v[36:37]
	v_mov_b32_e32 v76, v129
	s_mov_b64 s[50:51], s[46:47]
	s_mov_b64 s[2:3], s[44:45]
	s_and_saveexec_b64 s[8:9], s[48:49]
	s_cbranch_execz .LBB0_422
	s_branch .LBB0_432

.LBB0_445:
	s_andn2_saveexec_b64 s[2:3], s[2:3]
	s_or_b64 exec, exec, s[2:3]
	v_max3_f32 v142, v141, v146, v147
	v_mul_f32_e32 v143, 0x3e38aa3b, v142
	v_cmp_ngt_f32_e32 vcc, s36, v142
	v_sub_f32_e32 v141, v141, v142
	v_mul_f32_e32 v141, 0x3e38aa3b, v141
	v_cndmask_b32_e32 v143, 0, v143, vcc
	v_fma_f32 v128, v128, s29, -v143
	v_exp_f32_e32 v144, v128
	v_fma_f32 v129, v129, s29, -v143
	v_exp_f32_e32 v129, v129
	v_fma_f32 v130, v130, s29, -v143
	v_exp_f32_e32 v130, v130
	v_fma_f32 v131, v131, s29, -v143
	v_exp_f32_e32 v131, v131
	v_fma_f32 v124, v124, s29, -v143
	v_add_f32_e32 v128, 0, v144
	v_exp_f32_e32 v145, v124
	v_add_f32_e32 v128, v129, v128
	v_add_f32_e32 v128, v130, v128
	v_fma_f32 v125, v125, s29, -v143
	v_add_f32_e32 v128, v131, v128
	v_exp_f32_e32 v146, v125
	v_fma_f32 v125, v126, s29, -v143
	v_fma_f32 v117, v117, s29, -v143
	v_add_f32_e32 v124, v145, v128
	v_exp_f32_e32 v147, v125
	v_fma_f32 v125, v127, s29, -v143
	v_exp_f32_e32 v127, v117
	v_fma_f32 v117, v118, s29, -v143
	v_exp_f32_e32 v128, v141
	v_exp_f32_e32 v149, v117
	v_fma_f32 v117, v119, s29, -v143
	v_exp_f32_e32 v150, v117
	v_fma_f32 v117, v120, s29, -v143
	v_exp_f32_e32 v151, v117
	v_fma_f32 v117, v121, s29, -v143
	v_exp_f32_e32 v152, v117
	v_fma_f32 v117, v122, s29, -v143
	v_pk_mul_f32 v[120:121], v[88:89], v[128:129] op_sel_hi:[1,0]
	v_pk_mul_f32 v[88:89], v[92:93], v[128:129] op_sel_hi:[1,0]
	v_max_f32_e32 v92, v111, v111
	v_max_f32_e32 v93, v110, v110
	v_exp_f32_e32 v153, v117
	v_fma_f32 v117, v123, s29, -v143
	v_pk_mul_f32 v[122:123], v[90:91], v[128:129] op_sel_hi:[1,0]
	v_pk_mul_f32 v[90:91], v[94:95], v[128:129] op_sel_hi:[1,0]
	v_max_f32_e32 v92, v93, v92
	v_max_f32_e32 v93, v107, v107
	v_max_f32_e32 v94, v106, v106
	v_max_f32_e32 v93, v94, v93
	v_max3_f32 v92, v108, v109, v92
	v_max3_f32 v93, v104, v105, v93
	v_max3_f32 v92, v92, s28, v93
	v_max_f32_e32 v93, v103, v103
	v_max_f32_e32 v94, v102, v102
	v_max_f32_e32 v93, v94, v93
	v_max_f32_e32 v94, v115, v115
	v_max_f32_e32 v95, v114, v114
	v_max_f32_e32 v94, v95, v94
	v_exp_f32_e32 v148, v125
	v_fma_f32 v116, v116, s29, -v143
	v_max3_f32 v93, v100, v101, v93
	v_max3_f32 v94, v112, v113, v94
	v_exp_f32_e32 v126, v116
	v_max3_f32 v92, v92, v93, v94
	v_add_f32_e32 v124, v146, v124
	v_mov_b32_e32 v93, v92
	v_add_f32_e32 v124, v147, v124
	s_nop 0
	v_permlane16_swap_b32_e32 v92, v93
	v_add_f32_e32 v124, v148, v124
	v_max_f32_e32 v93, v93, v93
	v_max_f32_e32 v92, v92, v92
	v_add_f32_e32 v116, v126, v124
	v_max_f32_e32 v92, v92, v93
	v_add_f32_e32 v116, v127, v116
	v_mov_b32_e32 v93, v92
	v_add_f32_e32 v116, v149, v116
	s_nop 0
	v_permlane32_swap_b32_e32 v92, v93
	v_add_f32_e32 v116, v150, v116
	v_exp_f32_e32 v143, v117
	v_max3_f32 v125, v139, v92, v93
	v_add_f32_e32 v116, v151, v116
	v_mul_f32_e32 v93, 0x3e38aa3b, v125
	v_cmp_ngt_f32_e32 vcc, s36, v125
	v_add_f32_e32 v116, v152, v116
	v_add_f32_e32 v116, v153, v116
	v_cndmask_b32_e32 v93, 0, v93, vcc
	v_fma_f32 v94, v108, s29, -v93
	v_add_f32_e32 v124, v143, v116
	v_pk_mul_f32 v[116:117], v[84:85], v[128:129] op_sel_hi:[1,0]
	v_pk_mul_f32 v[84:85], v[96:97], v[128:129] op_sel_hi:[1,0]
	v_exp_f32_e32 v96, v94
	v_fma_f32 v95, v109, s29, -v93
	v_exp_f32_e32 v97, v95
	v_fma_f32 v95, v110, s29, -v93
	v_pk_mul_f32 v[118:119], v[86:87], v[128:129] op_sel_hi:[1,0]
	v_pk_mul_f32 v[86:87], v[98:99], v[128:129] op_sel_hi:[1,0]
	v_exp_f32_e32 v98, v95
	v_fma_f32 v95, v111, s29, -v93
	v_exp_f32_e32 v99, v95
	v_fma_f32 v95, v104, s29, -v93
	v_add_f32_e32 v94, 0, v96
	v_exp_f32_e32 v104, v95
	v_fma_f32 v95, v105, s29, -v93
	v_add_f32_e32 v94, v97, v94
	v_exp_f32_e32 v105, v95
	v_fma_f32 v95, v106, s29, -v93
	v_add_f32_e32 v94, v98, v94
	v_exp_f32_e32 v106, v95
	v_fma_f32 v95, v107, s29, -v93
	v_add_f32_e32 v94, v99, v94
	v_exp_f32_e32 v107, v95
	v_fma_f32 v95, v100, s29, -v93
	v_fmac_f32_e32 v124, v140, v128
	v_add_f32_e32 v94, v104, v94
	v_exp_f32_e32 v128, v95
	v_fma_f32 v95, v101, s29, -v93
	v_sub_f32_e32 v92, v139, v125
	v_add_f32_e32 v94, v105, v94
	v_exp_f32_e32 v139, v95
	v_fma_f32 v95, v102, s29, -v93
	v_lshrrev_b32_e32 v1, 2, v1
	v_lshlrev_b32_e32 v0, 3, v0
	v_add_f32_e32 v94, v106, v94
	v_exp_f32_e32 v140, v95
	v_fma_f32 v95, v103, s29, -v93
	v_or_b32_e32 v1, v3, v1
	v_and_b32_e32 v0, 24, v0
	v_add_f32_e32 v94, v107, v94
	v_exp_f32_e32 v141, v95
	v_fma_f32 v95, v112, s29, -v93
	v_mad_i32_i24 v0, v1, s0, v0
	v_add_f32_e32 v94, v128, v94
	v_exp_f32_e32 v154, v95
	v_fma_f32 v95, v113, s29, -v93
	v_cvt_pk_bf16_f32 v96, v96, v97
	v_cvt_pk_bf16_f32 v97, v98, v99
	v_cvt_pk_bf16_f32 v98, v104, v105
	v_cvt_pk_bf16_f32 v99, v106, v107
	ds_read_b64_tr_b16 v[162:163], v0 offset:29952
	ds_read_b64_tr_b16 v[160:161], v0 offset:27648
	ds_read_b64_tr_b16 v[164:165], v0 offset:27680
	ds_read_b64_tr_b16 v[166:167], v0 offset:29984
	ds_read_b64_tr_b16 v[168:169], v0 offset:27712
	ds_read_b64_tr_b16 v[170:171], v0 offset:30016
	ds_read_b64_tr_b16 v[172:173], v0 offset:27744
	ds_read_b64_tr_b16 v[174:175], v0 offset:30048
	ds_read_b64_tr_b16 v[176:177], v0 offset:32256
	ds_read_b64_tr_b16 v[178:179], v0 offset:34560
	ds_read_b64_tr_b16 v[180:181], v0 offset:32288
	ds_read_b64_tr_b16 v[182:183], v0 offset:34592
	ds_read_b64_tr_b16 v[184:185], v0 offset:32320
	ds_read_b64_tr_b16 v[186:187], v0 offset:34624
	ds_read_b64_tr_b16 v[188:189], v0 offset:32352
	ds_read_b64_tr_b16 v[190:191], v0 offset:34656
	v_add_f32_e32 v94, v139, v94
	v_exp_f32_e32 v155, v95
	v_fma_f32 v95, v114, s29, -v93
	v_add_f32_e32 v94, v140, v94
	v_exp_f32_e32 v156, v95
	v_fma_f32 v93, v115, s29, -v93
	v_mul_f32_e32 v92, 0x3e38aa3b, v92
	v_add_f32_e32 v94, v141, v94
	v_exp_f32_e32 v157, v93
	v_add_f32_e32 v94, v154, v94
	v_exp_f32_e32 v92, v92
	v_add_f32_e32 v94, v155, v94
	v_add_f32_e32 v94, v156, v94
	v_add_f32_e32 v158, v157, v94
	v_fmac_f32_e32 v158, v137, v92
	v_pk_mul_f32 v[70:71], v[70:71], v[92:93] op_sel_hi:[1,0]
	v_pk_mul_f32 v[68:69], v[68:69], v[92:93] op_sel_hi:[1,0]
	v_pk_mul_f32 v[74:75], v[74:75], v[92:93] op_sel_hi:[1,0]
	v_pk_mul_f32 v[72:73], v[72:73], v[92:93] op_sel_hi:[1,0]
	v_pk_mul_f32 v[78:79], v[78:79], v[92:93] op_sel_hi:[1,0]
	v_pk_mul_f32 v[76:77], v[76:77], v[92:93] op_sel_hi:[1,0]
	v_pk_mul_f32 v[82:83], v[82:83], v[92:93] op_sel_hi:[1,0]
	v_pk_mul_f32 v[80:81], v[80:81], v[92:93] op_sel_hi:[1,0]
	v_cvt_pk_bf16_f32 v92, v144, v129
	v_cvt_pk_bf16_f32 v93, v130, v131
	v_cvt_pk_bf16_f32 v94, v145, v146
	v_cvt_pk_bf16_f32 v95, v147, v148
	s_waitcnt lgkmcnt(14)
	v_mfma_f32_16x16x32_bf16 v[68:71], v[160:163], v[96:99], v[68:71]
	v_mov_b32_e32 v137, v158
	v_mfma_f32_16x16x32_bf16 v[108:111], v[160:163], v[92:95], v[116:119]
	s_waitcnt lgkmcnt(12)
	v_mfma_f32_16x16x32_bf16 v[100:103], v[164:167], v[92:95], v[120:123]
	s_nop 0
	v_cvt_pk_bf16_f32 v116, v128, v139
	v_cvt_pk_bf16_f32 v117, v140, v141
	v_cvt_pk_bf16_f32 v118, v154, v155
	v_mfma_f32_16x16x32_bf16 v[72:75], v[164:167], v[96:99], v[72:75]
	v_cvt_pk_bf16_f32 v119, v156, v157
	v_mov_b32_e32 v141, v142
	s_waitcnt lgkmcnt(10)
	v_mfma_f32_16x16x32_bf16 v[112:115], v[168:171], v[92:95], v[88:91]
	s_nop 2
	v_mov_b32_e32 v140, v124
	v_mov_b32_e32 v139, v125
	v_mfma_f32_16x16x32_bf16 v[76:79], v[168:171], v[96:99], v[76:79]
	s_waitcnt lgkmcnt(8)
	v_mfma_f32_16x16x32_bf16 v[104:107], v[172:175], v[92:95], v[84:87]
	v_mfma_f32_16x16x32_bf16 v[80:83], v[172:175], v[96:99], v[80:83]
	v_cvt_pk_bf16_f32 v96, v126, v127
	v_cvt_pk_bf16_f32 v97, v149, v150
	v_cvt_pk_bf16_f32 v98, v151, v152
	v_cvt_pk_bf16_f32 v99, v153, v143
	s_waitcnt lgkmcnt(6)
	v_mfma_f32_16x16x32_bf16 v[68:71], v[176:179], v[116:119], v[68:71]
	v_mfma_f32_16x16x32_bf16 v[84:87], v[176:179], v[96:99], v[108:111]
	s_waitcnt lgkmcnt(4)
	v_mfma_f32_16x16x32_bf16 v[88:91], v[180:183], v[96:99], v[100:103]
	s_nop 2
	v_mfma_f32_16x16x32_bf16 v[72:75], v[180:183], v[116:119], v[72:75]
	s_waitcnt lgkmcnt(2)
	v_mfma_f32_16x16x32_bf16 v[92:95], v[184:187], v[96:99], v[112:115]
	v_mfma_f32_16x16x32_bf16 v[76:79], v[184:187], v[116:119], v[76:79]
	s_waitcnt lgkmcnt(0)
	v_mfma_f32_16x16x32_bf16 v[96:99], v[188:191], v[96:99], v[104:107]
	v_mfma_f32_16x16x32_bf16 v[80:83], v[188:191], v[116:119], v[80:83]

.LBB0_449:
	s_or_b64 exec, exec, s[2:3]
	v_lshlrev_b32_e32 v0, 7, v100
	v_add_u32_e32 v143, 0xffffff80, v0
	v_cmp_ge_i32_e64 s[38:39], v17, v143
	v_cmp_le_i32_e64 s[40:41], v19, v0
	s_and_b64 s[2:3], s[38:39], s[40:41]
	s_and_saveexec_b64 s[48:49], s[2:3]
	s_cbranch_execz .LBB0_455
	v_mov_b32_e32 v1, v197
	v_cmp_gt_i32_e64 s[38:39], v0, v138
	v_and_b32_e32 v3, 15, v1
	v_mul_u32_u24_e32 v100, 0x48, v3
	v_bfe_u32 v144, v1, 4, 2
	v_lshlrev_b32_e32 v100, 1, v100
	v_lshl_add_u32 v142, v144, 4, v100
	ds_read_b128 v[160:163], v142 offset:2304
	ds_read_b128 v[164:167], v142 offset:0
	ds_read_b128 v[168:171], v142 offset:4608
	ds_read_b128 v[172:175], v142 offset:6912
	ds_read_b128 v[176:179], v142 offset:64
	ds_read_b128 v[180:183], v142 offset:2368
	ds_read_b128 v[184:187], v142 offset:6976
	ds_read_b128 v[188:191], v142 offset:4672
	v_cmp_gt_i32_e64 s[40:41], v17, v0
	s_or_b64 s[2:3], s[40:41], s[38:39]
	v_or_b32_e32 v145, v3, v13
	s_waitcnt lgkmcnt(7)
	v_mfma_f32_16x16x32_bf16 v[112:115], v[160:163], v[20:23], 0
	v_mfma_f32_16x16x32_bf16 v[116:119], v[160:163], v[28:31], 0
	s_waitcnt lgkmcnt(5)
	v_mfma_f32_16x16x32_bf16 v[120:123], v[168:171], v[20:23], 0
	v_mfma_f32_16x16x32_bf16 v[146:149], v[168:171], v[28:31], 0
	s_waitcnt lgkmcnt(4)
	v_mfma_f32_16x16x32_bf16 v[150:153], v[172:175], v[20:23], 0
	v_mfma_f32_16x16x32_bf16 v[154:157], v[172:175], v[28:31], 0
	v_mfma_f32_16x16x32_bf16 v[104:107], v[164:167], v[20:23], 0
	v_mfma_f32_16x16x32_bf16 v[100:103], v[164:167], v[28:31], 0
	s_waitcnt lgkmcnt(3)
	v_mfma_f32_16x16x32_bf16 v[128:131], v[176:179], v[24:27], v[104:107]
	v_mfma_f32_16x16x32_bf16 v[108:111], v[176:179], v[32:35], v[100:103]
	s_nop 4
	s_waitcnt lgkmcnt(2)
	v_mfma_f32_16x16x32_bf16 v[124:127], v[180:183], v[24:27], v[112:115]
	s_nop 2
	v_mfma_f32_16x16x32_bf16 v[104:107], v[180:183], v[32:35], v[116:119]
	v_lshlrev_b32_e32 v142, 2, v144
	s_waitcnt lgkmcnt(0)
	v_mfma_f32_16x16x32_bf16 v[116:119], v[188:191], v[24:27], v[120:123]
	v_mfma_f32_16x16x32_bf16 v[100:103], v[188:191], v[32:35], v[146:149]
	v_mfma_f32_16x16x32_bf16 v[120:123], v[184:187], v[24:27], v[150:153]
	v_mfma_f32_16x16x32_bf16 v[112:115], v[184:187], v[32:35], v[154:157]
	s_and_saveexec_b64 s[8:9], s[2:3]
	s_cbranch_execz .LBB0_452
	v_lshlrev_b32_e32 v146, 2, v144
	v_sub_u32_e32 v147, v145, v146
	v_cmp_ge_i32_e64 s[38:39], v147, v143
	v_cmp_le_i32_e64 s[40:41], v147, v0
	s_and_b64 s[38:39], s[38:39], s[40:41]
	v_xad_u32 v147, v146, -1, v145
	v_cndmask_b32_e64 v128, v212, v128, s[38:39]
	v_cmp_ge_i32_e64 s[38:39], v147, v143
	v_cmp_le_i32_e64 s[40:41], v147, v0
	v_or_b32_e32 v147, 2, v146
	s_and_b64 s[38:39], s[38:39], s[40:41]
	v_sub_u32_e32 v147, v145, v147
	v_cndmask_b32_e64 v129, v212, v129, s[38:39]
	v_cmp_ge_i32_e64 s[38:39], v147, v143
	v_cmp_le_i32_e64 s[40:41], v147, v0
	v_or_b32_e32 v147, 3, v146
	s_and_b64 s[38:39], s[38:39], s[40:41]
	v_sub_u32_e32 v147, v145, v147
	v_cndmask_b32_e64 v130, v212, v130, s[38:39]
	v_cmp_ge_i32_e64 s[38:39], v147, v143
	v_cmp_le_i32_e64 s[40:41], v147, v0
	v_or_b32_e32 v147, 16, v146
	s_and_b64 s[38:39], s[38:39], s[40:41]
	v_sub_u32_e32 v147, v145, v147
	v_cndmask_b32_e64 v131, v212, v131, s[38:39]
	v_cmp_ge_i32_e64 s[38:39], v147, v143
	v_cmp_le_i32_e64 s[40:41], v147, v0
	v_or_b32_e32 v147, 17, v146
	s_and_b64 s[38:39], s[38:39], s[40:41]
	v_sub_u32_e32 v147, v145, v147
	v_cndmask_b32_e64 v124, v212, v124, s[38:39]
	v_cmp_ge_i32_e64 s[38:39], v147, v143
	v_cmp_le_i32_e64 s[40:41], v147, v0
	v_or_b32_e32 v147, 18, v146
	s_and_b64 s[38:39], s[38:39], s[40:41]
	v_sub_u32_e32 v147, v145, v147
	v_cndmask_b32_e64 v125, v212, v125, s[38:39]
	v_cmp_ge_i32_e64 s[38:39], v147, v143
	v_cmp_le_i32_e64 s[40:41], v147, v0
	v_or_b32_e32 v147, 19, v146
	s_and_b64 s[38:39], s[38:39], s[40:41]
	v_sub_u32_e32 v147, v145, v147
	v_cndmask_b32_e64 v126, v212, v126, s[38:39]
	v_cmp_ge_i32_e64 s[38:39], v147, v143
	v_cmp_le_i32_e64 s[40:41], v147, v0
	v_or_b32_e32 v147, 32, v146
	s_and_b64 s[38:39], s[38:39], s[40:41]
	v_sub_u32_e32 v147, v145, v147
	v_cndmask_b32_e64 v127, v212, v127, s[38:39]
	v_cmp_ge_i32_e64 s[38:39], v147, v143
	v_cmp_le_i32_e64 s[40:41], v147, v0
	v_or_b32_e32 v147, 33, v146
	s_and_b64 s[38:39], s[38:39], s[40:41]
	v_sub_u32_e32 v147, v145, v147
	v_cndmask_b32_e64 v116, v212, v116, s[38:39]
	v_cmp_ge_i32_e64 s[38:39], v147, v143
	v_cmp_le_i32_e64 s[40:41], v147, v0
	v_or_b32_e32 v147, 34, v146
	s_and_b64 s[38:39], s[38:39], s[40:41]
	v_sub_u32_e32 v147, v145, v147
	v_cndmask_b32_e64 v117, v212, v117, s[38:39]
	v_cmp_ge_i32_e64 s[38:39], v147, v143
	v_cmp_le_i32_e64 s[40:41], v147, v0
	v_or_b32_e32 v147, 35, v146
	s_and_b64 s[38:39], s[38:39], s[40:41]
	v_sub_u32_e32 v147, v145, v147
	v_cndmask_b32_e64 v118, v212, v118, s[38:39]
	v_cmp_ge_i32_e64 s[38:39], v147, v143
	v_cmp_le_i32_e64 s[40:41], v147, v0
	v_or_b32_e32 v147, 48, v146
	s_and_b64 s[38:39], s[38:39], s[40:41]
	v_sub_u32_e32 v147, v145, v147
	v_cndmask_b32_e64 v119, v212, v119, s[38:39]
	v_cmp_ge_i32_e64 s[38:39], v147, v143
	v_cmp_le_i32_e64 s[40:41], v147, v0
	v_or_b32_e32 v147, 49, v146
	s_and_b64 s[38:39], s[38:39], s[40:41]
	v_sub_u32_e32 v147, v145, v147
	v_cndmask_b32_e64 v120, v212, v120, s[38:39]
	v_cmp_ge_i32_e64 s[38:39], v147, v143
	v_cmp_le_i32_e64 s[40:41], v147, v0
	v_or_b32_e32 v147, 50, v146
	s_and_b64 s[38:39], s[38:39], s[40:41]
	v_sub_u32_e32 v147, v145, v147
	v_cndmask_b32_e64 v121, v212, v121, s[38:39]
	v_cmp_ge_i32_e64 s[38:39], v147, v143
	v_cmp_le_i32_e64 s[40:41], v147, v0
	v_or_b32_e32 v146, 51, v146
	s_and_b64 s[38:39], s[38:39], s[40:41]
	v_sub_u32_e32 v146, v145, v146
	v_cndmask_b32_e64 v122, v212, v122, s[38:39]
	v_cmp_ge_i32_e64 s[38:39], v146, v143
	v_cmp_le_i32_e64 s[40:41], v146, v0
	s_and_b64 s[38:39], s[38:39], s[40:41]
	v_cndmask_b32_e64 v123, v212, v123, s[38:39]

.LBB0_454:
	s_andn2_saveexec_b64 s[2:3], s[2:3]
	s_or_b64 exec, exec, s[2:3]
	v_max3_f32 v143, v141, v146, v147
	v_mul_f32_e32 v144, 0x3e38aa3b, v143
	v_cmp_ngt_f32_e64 s[38:39], s36, v143
	v_sub_f32_e32 v141, v141, v143
	v_mul_f32_e32 v141, 0x3e38aa3b, v141
	v_cndmask_b32_e64 v144, 0, v144, s[38:39]
	v_fma_f32 v128, v128, s29, -v144
	v_exp_f32_e32 v145, v128
	v_fma_f32 v129, v129, s29, -v144
	v_exp_f32_e32 v129, v129
	v_fma_f32 v130, v130, s29, -v144
	v_exp_f32_e32 v130, v130
	v_fma_f32 v131, v131, s29, -v144
	v_exp_f32_e32 v131, v131
	v_fma_f32 v124, v124, s29, -v144
	v_add_f32_e32 v128, 0, v145
	v_exp_f32_e32 v146, v124
	v_add_f32_e32 v128, v129, v128
	v_add_f32_e32 v128, v130, v128
	v_fma_f32 v125, v125, s29, -v144
	v_add_f32_e32 v128, v131, v128
	v_exp_f32_e32 v147, v125
	v_fma_f32 v125, v126, s29, -v144
	v_fma_f32 v117, v117, s29, -v144
	v_add_f32_e32 v124, v146, v128
	v_exp_f32_e32 v148, v125
	v_fma_f32 v125, v127, s29, -v144
	v_exp_f32_e32 v127, v117
	v_fma_f32 v117, v118, s29, -v144
	v_exp_f32_e32 v128, v141
	v_exp_f32_e32 v150, v117
	v_fma_f32 v117, v119, s29, -v144
	v_exp_f32_e32 v151, v117
	v_fma_f32 v117, v120, s29, -v144
	v_exp_f32_e32 v152, v117
	v_fma_f32 v117, v121, s29, -v144
	v_exp_f32_e32 v153, v117
	v_fma_f32 v117, v122, s29, -v144
	v_pk_mul_f32 v[120:121], v[88:89], v[128:129] op_sel_hi:[1,0]
	v_pk_mul_f32 v[88:89], v[92:93], v[128:129] op_sel_hi:[1,0]
	v_max_f32_e32 v92, v111, v111
	v_max_f32_e32 v93, v110, v110
	v_exp_f32_e32 v154, v117
	v_fma_f32 v117, v123, s29, -v144
	v_pk_mul_f32 v[122:123], v[90:91], v[128:129] op_sel_hi:[1,0]
	v_pk_mul_f32 v[90:91], v[94:95], v[128:129] op_sel_hi:[1,0]
	v_max_f32_e32 v92, v93, v92
	v_max_f32_e32 v93, v107, v107
	v_max_f32_e32 v94, v106, v106
	v_max_f32_e32 v93, v94, v93
	v_max3_f32 v92, v108, v109, v92
	v_max3_f32 v93, v104, v105, v93
	v_max3_f32 v92, v92, s28, v93
	v_max_f32_e32 v93, v103, v103
	v_max_f32_e32 v94, v102, v102
	v_max_f32_e32 v93, v94, v93
	v_max_f32_e32 v94, v115, v115
	v_max_f32_e32 v95, v114, v114
	v_max_f32_e32 v94, v95, v94
	v_exp_f32_e32 v149, v125
	v_fma_f32 v116, v116, s29, -v144
	v_max3_f32 v93, v100, v101, v93
	v_max3_f32 v94, v112, v113, v94
	v_exp_f32_e32 v126, v116
	v_max3_f32 v92, v92, v93, v94
	v_add_f32_e32 v124, v147, v124
	v_mov_b32_e32 v93, v92
	v_add_f32_e32 v124, v148, v124
	s_nop 0
	v_permlane16_swap_b32_e32 v92, v93
	v_add_f32_e32 v124, v149, v124
	v_max_f32_e32 v93, v93, v93
	v_max_f32_e32 v92, v92, v92
	v_add_f32_e32 v116, v126, v124
	v_max_f32_e32 v92, v92, v93
	v_add_f32_e32 v116, v127, v116
	v_mov_b32_e32 v93, v92
	v_add_f32_e32 v116, v150, v116
	s_nop 0
	v_permlane32_swap_b32_e32 v92, v93
	v_add_f32_e32 v116, v151, v116
	v_exp_f32_e32 v144, v117
	v_max3_f32 v125, v139, v92, v93
	v_add_f32_e32 v116, v152, v116
	v_mul_f32_e32 v93, 0x3e38aa3b, v125
	v_cmp_ngt_f32_e64 s[38:39], s36, v125
	v_add_f32_e32 v116, v153, v116
	v_add_f32_e32 v116, v154, v116
	v_cndmask_b32_e64 v93, 0, v93, s[38:39]
	v_fma_f32 v94, v108, s29, -v93
	v_add_f32_e32 v124, v144, v116
	v_pk_mul_f32 v[116:117], v[84:85], v[128:129] op_sel_hi:[1,0]
	v_pk_mul_f32 v[84:85], v[96:97], v[128:129] op_sel_hi:[1,0]
	v_exp_f32_e32 v96, v94
	v_fma_f32 v95, v109, s29, -v93
	v_exp_f32_e32 v97, v95
	v_fma_f32 v95, v110, s29, -v93
	v_pk_mul_f32 v[118:119], v[86:87], v[128:129] op_sel_hi:[1,0]
	v_pk_mul_f32 v[86:87], v[98:99], v[128:129] op_sel_hi:[1,0]
	v_exp_f32_e32 v98, v95
	v_fma_f32 v95, v111, s29, -v93
	v_exp_f32_e32 v99, v95
	v_fma_f32 v95, v104, s29, -v93
	v_add_f32_e32 v94, 0, v96
	v_exp_f32_e32 v104, v95
	v_fma_f32 v95, v105, s29, -v93
	v_add_f32_e32 v94, v97, v94
	v_exp_f32_e32 v105, v95
	v_fma_f32 v95, v106, s29, -v93
	v_add_f32_e32 v94, v98, v94
	v_exp_f32_e32 v106, v95
	v_fma_f32 v95, v107, s29, -v93
	v_add_f32_e32 v94, v99, v94
	v_exp_f32_e32 v107, v95
	v_fma_f32 v95, v100, s29, -v93
	v_fmac_f32_e32 v124, v140, v128
	v_add_f32_e32 v94, v104, v94
	v_exp_f32_e32 v128, v95
	v_fma_f32 v95, v101, s29, -v93
	v_sub_f32_e32 v92, v139, v125
	v_add_f32_e32 v94, v105, v94
	v_exp_f32_e32 v139, v95
	v_fma_f32 v95, v102, s29, -v93
	v_lshrrev_b32_e32 v3, 2, v3
	v_lshlrev_b32_e32 v1, 3, v1
	v_add_f32_e32 v94, v106, v94
	v_exp_f32_e32 v140, v95
	v_fma_f32 v95, v103, s29, -v93
	v_or_b32_e32 v3, v142, v3
	v_and_b32_e32 v1, 24, v1
	v_add_f32_e32 v94, v107, v94
	v_exp_f32_e32 v141, v95
	v_fma_f32 v95, v112, s29, -v93
	v_mad_i32_i24 v1, v3, s0, v1
	v_add_f32_e32 v94, v128, v94
	v_exp_f32_e32 v155, v95
	v_fma_f32 v95, v113, s29, -v93
	v_cvt_pk_bf16_f32 v96, v96, v97
	v_cvt_pk_bf16_f32 v97, v98, v99
	v_cvt_pk_bf16_f32 v98, v104, v105
	v_cvt_pk_bf16_f32 v99, v106, v107
	ds_read_b64_tr_b16 v[162:163], v1 offset:20736
	ds_read_b64_tr_b16 v[160:161], v1 offset:18432
	ds_read_b64_tr_b16 v[164:165], v1 offset:18464
	ds_read_b64_tr_b16 v[166:167], v1 offset:20768
	ds_read_b64_tr_b16 v[168:169], v1 offset:18496
	ds_read_b64_tr_b16 v[170:171], v1 offset:20800
	ds_read_b64_tr_b16 v[172:173], v1 offset:18528
	ds_read_b64_tr_b16 v[174:175], v1 offset:20832
	ds_read_b64_tr_b16 v[176:177], v1 offset:23040
	ds_read_b64_tr_b16 v[178:179], v1 offset:25344
	ds_read_b64_tr_b16 v[180:181], v1 offset:23072
	ds_read_b64_tr_b16 v[182:183], v1 offset:25376
	ds_read_b64_tr_b16 v[184:185], v1 offset:23104
	ds_read_b64_tr_b16 v[186:187], v1 offset:25408
	ds_read_b64_tr_b16 v[188:189], v1 offset:23136
	ds_read_b64_tr_b16 v[190:191], v1 offset:25440
	v_add_f32_e32 v94, v139, v94
	v_exp_f32_e32 v156, v95
	v_fma_f32 v95, v114, s29, -v93
	v_add_f32_e32 v94, v140, v94
	v_exp_f32_e32 v157, v95
	v_fma_f32 v93, v115, s29, -v93
	v_mul_f32_e32 v92, 0x3e38aa3b, v92
	v_add_f32_e32 v94, v141, v94
	v_exp_f32_e32 v158, v93
	v_add_f32_e32 v94, v155, v94
	v_exp_f32_e32 v92, v92
	v_add_f32_e32 v94, v156, v94
	v_add_f32_e32 v94, v157, v94
	v_add_f32_e32 v159, v158, v94
	v_fmac_f32_e32 v159, v137, v92
	v_pk_mul_f32 v[70:71], v[70:71], v[92:93] op_sel_hi:[1,0]
	v_pk_mul_f32 v[68:69], v[68:69], v[92:93] op_sel_hi:[1,0]
	v_pk_mul_f32 v[74:75], v[74:75], v[92:93] op_sel_hi:[1,0]
	v_pk_mul_f32 v[72:73], v[72:73], v[92:93] op_sel_hi:[1,0]
	v_pk_mul_f32 v[78:79], v[78:79], v[92:93] op_sel_hi:[1,0]
	v_pk_mul_f32 v[76:77], v[76:77], v[92:93] op_sel_hi:[1,0]
	v_pk_mul_f32 v[82:83], v[82:83], v[92:93] op_sel_hi:[1,0]
	v_pk_mul_f32 v[80:81], v[80:81], v[92:93] op_sel_hi:[1,0]
	v_cvt_pk_bf16_f32 v92, v145, v129
	v_cvt_pk_bf16_f32 v93, v130, v131
	v_cvt_pk_bf16_f32 v94, v146, v147
	v_cvt_pk_bf16_f32 v95, v148, v149
	s_waitcnt lgkmcnt(14)
	v_mfma_f32_16x16x32_bf16 v[68:71], v[160:163], v[96:99], v[68:71]
	v_mov_b32_e32 v137, v159
	v_mfma_f32_16x16x32_bf16 v[108:111], v[160:163], v[92:95], v[116:119]
	s_waitcnt lgkmcnt(12)
	v_mfma_f32_16x16x32_bf16 v[100:103], v[164:167], v[92:95], v[120:123]
	s_nop 0
	v_cvt_pk_bf16_f32 v116, v128, v139
	v_cvt_pk_bf16_f32 v117, v140, v141
	v_cvt_pk_bf16_f32 v118, v155, v156
	v_mfma_f32_16x16x32_bf16 v[72:75], v[164:167], v[96:99], v[72:75]
	v_cvt_pk_bf16_f32 v119, v157, v158
	v_mov_b32_e32 v141, v143
	s_waitcnt lgkmcnt(10)
	v_mfma_f32_16x16x32_bf16 v[112:115], v[168:171], v[92:95], v[88:91]
	s_nop 2
	v_mov_b32_e32 v140, v124
	v_mov_b32_e32 v139, v125
	v_mfma_f32_16x16x32_bf16 v[76:79], v[168:171], v[96:99], v[76:79]
	s_waitcnt lgkmcnt(8)
	v_mfma_f32_16x16x32_bf16 v[104:107], v[172:175], v[92:95], v[84:87]
	v_mfma_f32_16x16x32_bf16 v[80:83], v[172:175], v[96:99], v[80:83]
	v_cvt_pk_bf16_f32 v96, v126, v127
	v_cvt_pk_bf16_f32 v97, v150, v151
	v_cvt_pk_bf16_f32 v98, v152, v153
	v_cvt_pk_bf16_f32 v99, v154, v144
	s_waitcnt lgkmcnt(6)
	v_mfma_f32_16x16x32_bf16 v[68:71], v[176:179], v[116:119], v[68:71]
	v_mfma_f32_16x16x32_bf16 v[84:87], v[176:179], v[96:99], v[108:111]
	s_waitcnt lgkmcnt(4)
	v_mfma_f32_16x16x32_bf16 v[88:91], v[180:183], v[96:99], v[100:103]
	s_nop 2
	v_mfma_f32_16x16x32_bf16 v[72:75], v[180:183], v[116:119], v[72:75]
	s_waitcnt lgkmcnt(2)
	v_mfma_f32_16x16x32_bf16 v[92:95], v[184:187], v[96:99], v[112:115]
	v_mfma_f32_16x16x32_bf16 v[76:79], v[184:187], v[116:119], v[76:79]
	s_waitcnt lgkmcnt(0)
	v_mfma_f32_16x16x32_bf16 v[96:99], v[188:191], v[96:99], v[104:107]
	v_mfma_f32_16x16x32_bf16 v[80:83], v[188:191], v[116:119], v[80:83]
.LBB0_455:
	s_or_b64 exec, exec, s[48:49]
	s_and_b64 s[2:3], exec, vcc
	v_or_b32_e32 v142, 64, v0
	v_subrev_u32_e32 v143, 64, v0
	s_or_b64 s[46:47], s[2:3], s[46:47]
	v_cmp_ge_i32_e32 vcc, v17, v143
	v_cmp_le_i32_e64 s[38:39], v19, v142
	s_and_b64 s[2:3], vcc, s[38:39]
	s_and_saveexec_b64 s[40:41], s[2:3]
	s_cbranch_execz .LBB0_446
	v_mov_b32_e32 v0, v197
	v_cmp_gt_i32_e32 vcc, v142, v138
	v_and_b32_e32 v1, 15, v0
	v_mul_u32_u24_e32 v3, 0x48, v1
	v_bfe_u32 v144, v0, 4, 2
	v_lshlrev_b32_e32 v3, 1, v3
	v_lshl_add_u32 v3, v144, 4, v3
	ds_read_b128 v[160:163], v3 offset:11520
	ds_read_b128 v[164:167], v3 offset:9216
	ds_read_b128 v[168:171], v3 offset:13824
	ds_read_b128 v[172:175], v3 offset:16128
	ds_read_b128 v[176:179], v3 offset:9280
	ds_read_b128 v[180:183], v3 offset:11584
	ds_read_b128 v[184:187], v3 offset:16192
	ds_read_b128 v[188:191], v3 offset:13888
	v_cmp_gt_i32_e64 s[38:39], v17, v142
	s_or_b64 s[2:3], s[38:39], vcc
	v_or_b32_e32 v145, v1, v13
	s_waitcnt lgkmcnt(7)
	v_mfma_f32_16x16x32_bf16 v[112:115], v[160:163], v[20:23], 0
	v_mfma_f32_16x16x32_bf16 v[116:119], v[160:163], v[28:31], 0
	s_waitcnt lgkmcnt(5)
	v_mfma_f32_16x16x32_bf16 v[120:123], v[168:171], v[20:23], 0
	v_mfma_f32_16x16x32_bf16 v[146:149], v[168:171], v[28:31], 0
	s_waitcnt lgkmcnt(4)
	v_mfma_f32_16x16x32_bf16 v[150:153], v[172:175], v[20:23], 0
	v_mfma_f32_16x16x32_bf16 v[154:157], v[172:175], v[28:31], 0
	v_mfma_f32_16x16x32_bf16 v[104:107], v[164:167], v[20:23], 0
	v_mfma_f32_16x16x32_bf16 v[100:103], v[164:167], v[28:31], 0
	s_waitcnt lgkmcnt(3)
	v_mfma_f32_16x16x32_bf16 v[128:131], v[176:179], v[24:27], v[104:107]
	v_mfma_f32_16x16x32_bf16 v[108:111], v[176:179], v[32:35], v[100:103]
	s_nop 4
	s_waitcnt lgkmcnt(2)
	v_mfma_f32_16x16x32_bf16 v[124:127], v[180:183], v[24:27], v[112:115]
	s_nop 2
	v_mfma_f32_16x16x32_bf16 v[104:107], v[180:183], v[32:35], v[116:119]
	v_lshlrev_b32_e32 v3, 2, v144
	s_waitcnt lgkmcnt(0)
	v_mfma_f32_16x16x32_bf16 v[116:119], v[188:191], v[24:27], v[120:123]
	v_mfma_f32_16x16x32_bf16 v[100:103], v[188:191], v[32:35], v[146:149]
	v_mfma_f32_16x16x32_bf16 v[120:123], v[184:187], v[24:27], v[150:153]
	v_mfma_f32_16x16x32_bf16 v[112:115], v[184:187], v[32:35], v[154:157]
	s_and_saveexec_b64 s[8:9], s[2:3]
	s_cbranch_execz .LBB0_458
	v_lshlrev_b32_e32 v146, 2, v144
	v_sub_u32_e32 v147, v145, v146
	v_cmp_ge_i32_e32 vcc, v147, v143
	v_cmp_le_i32_e64 s[38:39], v147, v142
	s_and_b64 vcc, vcc, s[38:39]
	v_xad_u32 v147, v146, -1, v145
	v_cndmask_b32_e32 v128, v212, v128, vcc
	v_cmp_ge_i32_e32 vcc, v147, v143
	v_cmp_le_i32_e64 s[38:39], v147, v142
	v_or_b32_e32 v147, 2, v146
	s_and_b64 vcc, vcc, s[38:39]
	v_sub_u32_e32 v147, v145, v147
	v_cndmask_b32_e32 v129, v212, v129, vcc
	v_cmp_ge_i32_e32 vcc, v147, v143
	v_cmp_le_i32_e64 s[38:39], v147, v142
	v_or_b32_e32 v147, 3, v146
	s_and_b64 vcc, vcc, s[38:39]
	v_sub_u32_e32 v147, v145, v147
	v_cndmask_b32_e32 v130, v212, v130, vcc
	v_cmp_ge_i32_e32 vcc, v147, v143
	v_cmp_le_i32_e64 s[38:39], v147, v142
	v_or_b32_e32 v147, 16, v146
	s_and_b64 vcc, vcc, s[38:39]
	v_sub_u32_e32 v147, v145, v147
	v_cndmask_b32_e32 v131, v212, v131, vcc
	v_cmp_ge_i32_e32 vcc, v147, v143
	v_cmp_le_i32_e64 s[38:39], v147, v142
	v_or_b32_e32 v147, 17, v146
	s_and_b64 vcc, vcc, s[38:39]
	v_sub_u32_e32 v147, v145, v147
	v_cndmask_b32_e32 v124, v212, v124, vcc
	v_cmp_ge_i32_e32 vcc, v147, v143
	v_cmp_le_i32_e64 s[38:39], v147, v142
	v_or_b32_e32 v147, 18, v146
	s_and_b64 vcc, vcc, s[38:39]
	v_sub_u32_e32 v147, v145, v147
	v_cndmask_b32_e32 v125, v212, v125, vcc
	v_cmp_ge_i32_e32 vcc, v147, v143
	v_cmp_le_i32_e64 s[38:39], v147, v142
	v_or_b32_e32 v147, 19, v146
	s_and_b64 vcc, vcc, s[38:39]
	v_sub_u32_e32 v147, v145, v147
	v_cndmask_b32_e32 v126, v212, v126, vcc
	v_cmp_ge_i32_e32 vcc, v147, v143
	v_cmp_le_i32_e64 s[38:39], v147, v142
	v_or_b32_e32 v147, 32, v146
	s_and_b64 vcc, vcc, s[38:39]
	v_sub_u32_e32 v147, v145, v147
	v_cndmask_b32_e32 v127, v212, v127, vcc
	v_cmp_ge_i32_e32 vcc, v147, v143
	v_cmp_le_i32_e64 s[38:39], v147, v142
	v_or_b32_e32 v147, 33, v146
	s_and_b64 vcc, vcc, s[38:39]
	v_sub_u32_e32 v147, v145, v147
	v_cndmask_b32_e32 v116, v212, v116, vcc
	v_cmp_ge_i32_e32 vcc, v147, v143
	v_cmp_le_i32_e64 s[38:39], v147, v142
	v_or_b32_e32 v147, 34, v146
	s_and_b64 vcc, vcc, s[38:39]
	v_sub_u32_e32 v147, v145, v147
	v_cndmask_b32_e32 v117, v212, v117, vcc
	v_cmp_ge_i32_e32 vcc, v147, v143
	v_cmp_le_i32_e64 s[38:39], v147, v142
	v_or_b32_e32 v147, 35, v146
	s_and_b64 vcc, vcc, s[38:39]
	v_sub_u32_e32 v147, v145, v147
	v_cndmask_b32_e32 v118, v212, v118, vcc
	v_cmp_ge_i32_e32 vcc, v147, v143
	v_cmp_le_i32_e64 s[38:39], v147, v142
	v_or_b32_e32 v147, 48, v146
	s_and_b64 vcc, vcc, s[38:39]
	v_sub_u32_e32 v147, v145, v147
	v_cndmask_b32_e32 v119, v212, v119, vcc
	v_cmp_ge_i32_e32 vcc, v147, v143
	v_cmp_le_i32_e64 s[38:39], v147, v142
	v_or_b32_e32 v147, 49, v146
	s_and_b64 vcc, vcc, s[38:39]
	v_sub_u32_e32 v147, v145, v147
	v_cndmask_b32_e32 v120, v212, v120, vcc
	v_cmp_ge_i32_e32 vcc, v147, v143
	v_cmp_le_i32_e64 s[38:39], v147, v142
	v_or_b32_e32 v147, 50, v146
	s_and_b64 vcc, vcc, s[38:39]
	v_sub_u32_e32 v147, v145, v147
	v_cndmask_b32_e32 v121, v212, v121, vcc
	v_cmp_ge_i32_e32 vcc, v147, v143
	v_cmp_le_i32_e64 s[38:39], v147, v142
	v_or_b32_e32 v146, 51, v146
	s_and_b64 vcc, vcc, s[38:39]
	v_sub_u32_e32 v146, v145, v146
	v_cndmask_b32_e32 v122, v212, v122, vcc
	v_cmp_ge_i32_e32 vcc, v146, v143
	v_cmp_le_i32_e64 s[38:39], v146, v142
	s_and_b64 vcc, vcc, s[38:39]
	v_cndmask_b32_e32 v123, v212, v123, vcc
